# attnC unit epilogue: O tiles transposed through LDS, full 128-byte row stores (was 16 eight-byte-piece stores per wave)
# speedup vs baseline: 1.1287x; 1.0090x over previous
; __device__ __forceinline__ unsigned pk2(float lo, float hi) { unsigned r; asm("v_cvt_pk_bf16_f32 %0, %1, %2" : "=v"(r) : "v"(lo), "v"(hi)); return r; }
; __device__ __forceinline__ void attnC_unit(const Args& a, int unit, LAS unsigned char* lds) {
;     ...
; #pragma unroll
;     for (int e = 0; e < 2; ++e) {
;         const float lt = l[e] + __shfl_xor(l[e], 32), inv = 1.0f / lt;
;         bf16_t* op = MIX + (tok0 + 32 * e) * DM + 640 + 64 * hq;
; #pragma unroll
;         for (int dt = 0; dt < 2; ++dt)
; #pragma unroll
;             for (int gg = 0; gg < 4; ++gg) {
;                 const f32x16& oo = dt ? o1[e] : o0[e];
;                 u32x2 w; w.x = pk2(oo[4 * gg] * inv, oo[4 * gg + 1] * inv); w.y = pk2(oo[4 * gg + 2] * inv, oo[4 * gg + 3] * inv);
;                 *(u32x2*)(op + 32 * dt + 8 * gg + 4 * h) = w;
;             }
;     }
.LBB0_252:
	v_and_b32_e32 v120, 31, v225
	v_bfe_u32 v121, v225, 3, 3
	v_and_b32_e32 v122, 7, v225
	v_lshlrev_b32_e32 v122, 4, v122
	v_lshlrev_b32_e32 v154, 3, v249
	v_readfirstlane_b32 s2, v225
	s_lshl_b32 s2, s2, 6
	s_add_i32 s2, s2, 0x10000
	v_and_b32_e32 v123, 7, v120
	v_lshlrev_b32_e32 v123, 4, v123
	v_lshl_or_b32 v123, v120, 7, v123
	v_or_b32_e32 v123, v123, v154
	v_add_u32_e32 v123, s2, v123
	v_lshlrev_b32_e32 v124, 4, v121
	v_xor_b32_e32 v124, v124, v122
	v_lshl_add_u32 v124, v121, 7, v124
	v_add_u32_e32 v124, s2, v124
	v_sub_u32_e32 v125, v176, v120
	v_add_u32_e32 v125, v125, v121
	s_lshl_b64 s[0:1], s[0:1], 1
	s_add_u32 s2, s24, s22
	s_addc_u32 s3, s25, s23
	s_add_u32 s2, s2, s0
	s_addc_u32 s3, s3, s1
	v_mov_b32_e32 v126, s2
	v_mov_b32_e32 v127, s3
	v_add_co_u32_e32 v126, vcc, v126, v122
	s_movk_i32 s4, 0x800
	v_addc_co_u32_e32 v127, vcc, 0, v127, vcc
	v_mov_b32_e32 v128, v179
	s_nop 1
	v_permlane32_swap_b32_e32 v128, v179
	v_add_f32_e32 v129, v179, v128
	v_div_scale_f32 v131, s[10:11], v129, v129, 1.0
	v_rcp_f32_e32 v132, v131
	v_div_scale_f32 v133, vcc, 1.0, v129, 1.0
	v_fma_f32 v134, -v131, v132, 1.0
	v_fmac_f32_e32 v132, v134, v132
	v_mul_f32_e32 v134, v133, v132
	v_fma_f32 v130, -v131, v134, v133
	v_fmac_f32_e32 v134, v130, v132
	v_fma_f32 v131, -v131, v134, v133
	v_div_fmas_f32 v131, v131, v132, v134
	v_div_fixup_f32 v130, v131, v129, 1.0
	v_mul_f32_e32 v140, v48, v130
	v_mul_f32_e32 v141, v49, v130
	v_mul_f32_e32 v142, v50, v130
	v_mul_f32_e32 v143, v51, v130
	v_cvt_pk_bf16_f32 v136, v140, v141
	v_cvt_pk_bf16_f32 v137, v142, v143
	v_xor_b32_e32 v135, 0x0, v123
	ds_write_b64 v135, v[136:137]
	v_mul_f32_e32 v140, v52, v130
	v_mul_f32_e32 v141, v53, v130
	v_mul_f32_e32 v142, v54, v130
	v_mul_f32_e32 v143, v55, v130
	v_cvt_pk_bf16_f32 v138, v140, v141
	v_cvt_pk_bf16_f32 v139, v142, v143
	v_xor_b32_e32 v135, 0x10, v123
	ds_write_b64 v135, v[138:139]
	v_mul_f32_e32 v140, v56, v130
	v_mul_f32_e32 v141, v57, v130
	v_mul_f32_e32 v142, v58, v130
	v_mul_f32_e32 v143, v59, v130
	v_cvt_pk_bf16_f32 v136, v140, v141
	v_cvt_pk_bf16_f32 v137, v142, v143
	v_xor_b32_e32 v135, 0x20, v123
	ds_write_b64 v135, v[136:137]
	v_mul_f32_e32 v140, v60, v130
	v_mul_f32_e32 v141, v61, v130
	v_mul_f32_e32 v142, v62, v130
	v_mul_f32_e32 v143, v63, v130
	v_cvt_pk_bf16_f32 v138, v140, v141
	v_cvt_pk_bf16_f32 v139, v142, v143
	v_xor_b32_e32 v135, 0x30, v123
	ds_write_b64 v135, v[138:139]
	v_mul_f32_e32 v140, v32, v130
	v_mul_f32_e32 v141, v33, v130
	v_mul_f32_e32 v142, v34, v130
	v_mul_f32_e32 v143, v35, v130
	v_cvt_pk_bf16_f32 v136, v140, v141
	v_cvt_pk_bf16_f32 v137, v142, v143
	v_xor_b32_e32 v135, 0x40, v123
	ds_write_b64 v135, v[136:137]
	v_mul_f32_e32 v140, v36, v130
	v_mul_f32_e32 v141, v37, v130
	v_mul_f32_e32 v142, v38, v130
	v_mul_f32_e32 v143, v39, v130
	v_cvt_pk_bf16_f32 v138, v140, v141
	v_cvt_pk_bf16_f32 v139, v142, v143
	v_xor_b32_e32 v135, 0x50, v123
	ds_write_b64 v135, v[138:139]
	v_mul_f32_e32 v140, v40, v130
	v_mul_f32_e32 v141, v41, v130
	v_mul_f32_e32 v142, v42, v130
	v_mul_f32_e32 v143, v43, v130
	v_cvt_pk_bf16_f32 v136, v140, v141
	v_cvt_pk_bf16_f32 v137, v142, v143
	v_xor_b32_e32 v135, 0x60, v123
	ds_write_b64 v135, v[136:137]
	v_mul_f32_e32 v140, v44, v130
	v_mul_f32_e32 v141, v45, v130
	v_mul_f32_e32 v142, v46, v130
	v_mul_f32_e32 v143, v47, v130
	v_cvt_pk_bf16_f32 v138, v140, v141
	v_cvt_pk_bf16_f32 v139, v142, v143
	v_xor_b32_e32 v135, 0x70, v123
	ds_write_b64 v135, v[138:139]
	s_waitcnt lgkmcnt(0)
	ds_read_b128 v[64:67], v124
	ds_read_b128 v[68:71], v124 offset:1024
	ds_read_b128 v[72:75], v124 offset:2048
	ds_read_b128 v[76:79], v124 offset:3072
	v_add_u32_e32 v144, 0, v125
	v_mad_u64_u32 v[146:147], s[10:11], v144, s4, v[126:127]
	s_waitcnt lgkmcnt(3)
	global_store_dwordx4 v[146:147], v[64:67], off
	v_add_u32_e32 v144, 8, v125
	v_mad_u64_u32 v[148:149], s[10:11], v144, s4, v[126:127]
	s_waitcnt lgkmcnt(2)
; __device__ __forceinline__ unsigned pk2(float lo, float hi) { unsigned r; asm("v_cvt_pk_bf16_f32 %0, %1, %2" : "=v"(r) : "v"(lo), "v"(hi)); return r; }
; __device__ __forceinline__ void attnC_unit(const Args& a, int unit, LAS unsigned char* lds) {
;     ...
; #pragma unroll
;     for (int e = 0; e < 2; ++e) {
;         const float lt = l[e] + __shfl_xor(l[e], 32), inv = 1.0f / lt;
;         bf16_t* op = MIX + (tok0 + 32 * e) * DM + 640 + 64 * hq;
; #pragma unroll
;         for (int dt = 0; dt < 2; ++dt)
; #pragma unroll
;             for (int gg = 0; gg < 4; ++gg) {
;                 const f32x16& oo = dt ? o1[e] : o0[e];
;                 u32x2 w; w.x = pk2(oo[4 * gg] * inv, oo[4 * gg + 1] * inv); w.y = pk2(oo[4 * gg + 2] * inv, oo[4 * gg + 3] * inv);
;                 *(u32x2*)(op + 32 * dt + 8 * gg + 4 * h) = w;
;             }
;     }
	global_store_dwordx4 v[148:149], v[68:71], off
	v_add_u32_e32 v144, 16, v125
	v_mad_u64_u32 v[146:147], s[10:11], v144, s4, v[126:127]
	s_waitcnt lgkmcnt(1)
	global_store_dwordx4 v[146:147], v[72:75], off
	v_add_u32_e32 v144, 24, v125
	v_mad_u64_u32 v[148:149], s[10:11], v144, s4, v[126:127]
	s_waitcnt lgkmcnt(0)
	global_store_dwordx4 v[148:149], v[76:79], off
	v_mov_b32_e32 v128, v178
	s_nop 1
	v_permlane32_swap_b32_e32 v128, v178
	v_add_f32_e32 v129, v178, v128
	v_div_scale_f32 v131, s[10:11], v129, v129, 1.0
	v_rcp_f32_e32 v132, v131
	v_div_scale_f32 v133, vcc, 1.0, v129, 1.0
	v_fma_f32 v134, -v131, v132, 1.0
	v_fmac_f32_e32 v132, v134, v132
	v_mul_f32_e32 v134, v133, v132
	v_fma_f32 v130, -v131, v134, v133
	v_fmac_f32_e32 v134, v130, v132
	v_fma_f32 v131, -v131, v134, v133
	v_div_fmas_f32 v131, v131, v132, v134
	v_div_fixup_f32 v130, v131, v129, 1.0
	v_mul_f32_e32 v140, v16, v130
	v_mul_f32_e32 v141, v17, v130
	v_mul_f32_e32 v142, v18, v130
	v_mul_f32_e32 v143, v19, v130
	v_cvt_pk_bf16_f32 v136, v140, v141
	v_cvt_pk_bf16_f32 v137, v142, v143
	v_xor_b32_e32 v135, 0x0, v123
	ds_write_b64 v135, v[136:137]
	v_mul_f32_e32 v140, v20, v130
	v_mul_f32_e32 v141, v21, v130
	v_mul_f32_e32 v142, v22, v130
	v_mul_f32_e32 v143, v23, v130
	v_cvt_pk_bf16_f32 v138, v140, v141
	v_cvt_pk_bf16_f32 v139, v142, v143
	v_xor_b32_e32 v135, 0x10, v123
	ds_write_b64 v135, v[138:139]
	v_mul_f32_e32 v140, v24, v130
	v_mul_f32_e32 v141, v25, v130
	v_mul_f32_e32 v142, v26, v130
	v_mul_f32_e32 v143, v27, v130
	v_cvt_pk_bf16_f32 v136, v140, v141
	v_cvt_pk_bf16_f32 v137, v142, v143
	v_xor_b32_e32 v135, 0x20, v123
	ds_write_b64 v135, v[136:137]
	v_mul_f32_e32 v140, v28, v130
	v_mul_f32_e32 v141, v29, v130
	v_mul_f32_e32 v142, v30, v130
	v_mul_f32_e32 v143, v31, v130
	v_cvt_pk_bf16_f32 v138, v140, v141
	v_cvt_pk_bf16_f32 v139, v142, v143
	v_xor_b32_e32 v135, 0x30, v123
	ds_write_b64 v135, v[138:139]
	v_mul_f32_e32 v140, v0, v130
	v_mul_f32_e32 v141, v1, v130
	v_mul_f32_e32 v142, v2, v130
	v_mul_f32_e32 v143, v3, v130
	v_cvt_pk_bf16_f32 v136, v140, v141
	v_cvt_pk_bf16_f32 v137, v142, v143
	v_xor_b32_e32 v135, 0x40, v123
	ds_write_b64 v135, v[136:137]
	v_mul_f32_e32 v140, v4, v130
	v_mul_f32_e32 v141, v5, v130
	v_mul_f32_e32 v142, v6, v130
	v_mul_f32_e32 v143, v7, v130
	v_cvt_pk_bf16_f32 v138, v140, v141
	v_cvt_pk_bf16_f32 v139, v142, v143
	v_xor_b32_e32 v135, 0x50, v123
	ds_write_b64 v135, v[138:139]
	v_mul_f32_e32 v140, v8, v130
	v_mul_f32_e32 v141, v9, v130
	v_mul_f32_e32 v142, v10, v130
	v_mul_f32_e32 v143, v11, v130
	v_cvt_pk_bf16_f32 v136, v140, v141
	v_cvt_pk_bf16_f32 v137, v142, v143
	v_xor_b32_e32 v135, 0x60, v123
	ds_write_b64 v135, v[136:137]
	v_mul_f32_e32 v140, v12, v130
	v_mul_f32_e32 v141, v13, v130
	v_mul_f32_e32 v142, v14, v130
	v_mul_f32_e32 v143, v15, v130
	v_cvt_pk_bf16_f32 v138, v140, v141
	v_cvt_pk_bf16_f32 v139, v142, v143
	v_xor_b32_e32 v135, 0x70, v123
	ds_write_b64 v135, v[138:139]
	s_waitcnt lgkmcnt(0)
	ds_read_b128 v[64:67], v124
	ds_read_b128 v[68:71], v124 offset:1024
	ds_read_b128 v[72:75], v124 offset:2048
	ds_read_b128 v[76:79], v124 offset:3072
	v_add_u32_e32 v144, 32, v125
	v_mad_u64_u32 v[146:147], s[10:11], v144, s4, v[126:127]
	s_waitcnt lgkmcnt(3)
	global_store_dwordx4 v[146:147], v[64:67], off
	v_add_u32_e32 v144, 40, v125
	v_mad_u64_u32 v[148:149], s[10:11], v144, s4, v[126:127]
	s_waitcnt lgkmcnt(2)
	global_store_dwordx4 v[148:149], v[68:71], off
	v_add_u32_e32 v144, 48, v125
	v_mad_u64_u32 v[146:147], s[10:11], v144, s4, v[126:127]
	s_waitcnt lgkmcnt(1)
	global_store_dwordx4 v[146:147], v[72:75], off
	v_add_u32_e32 v144, 56, v125
	v_mad_u64_u32 v[148:149], s[10:11], v144, s4, v[126:127]
	s_waitcnt lgkmcnt(0)
	global_store_dwordx4 v[148:149], v[76:79], off
	s_add_i32 s8, s8, 1
	s_cmp_eq_u32 s8, 3
	s_cbranch_scc1 .LBB0_259
